# sparse-attention selected-block loop: hand-scheduled body (Q.K MFMAs of one N-tile between the softmax VALU of the other)
# speedup vs baseline: 1.0226x; 1.0083x over previous
;     ...
;   if (kt >= kt_end) { hook(); return; }
;   const bf16x8 ones = bf16x8{0x3F80, 0x3F80, 0x3F80, 0x3F80, 0x3F80, 0x3F80, 0x3F80, 0x3F80};
;   f32x4 L[NQ * NMAP];
; #pragma unroll
;   for (int i = 0; i < NQ * NMAP; ++i) L[i] = f32x4{0.f, 0.f, 0.f, 0.f};
;   int nxt = next_tile(kt);
;   {
;     u32x4 fk[TK][2], fv[TK][2];
; #pragma unroll
;     for (int t = 0; t < TK; ++t)
; #pragma unroll
;       for (int i = 0; i < 2; ++i) {
;         fk[t][i] = *(const u32x4*)(gk + (size_t)((kt + t) * 64 + i * 32) * kstride);
;         fv[t][i] = *(const u32x4*)(gv + (size_t)(i * 32) * vtstride + (kt + t) * 64);
;       }
;     if (nxt < kt_end) gload(nxt);
;     hook();
;     __syncthreads();
; #pragma unroll
;     for (int t = 0; t < TK; ++t)
; #pragma unroll
;       for (int i = 0; i < 2; ++i) {
;         *(u32x4*)(wk + t * TSZ + i * 32 * 64) = fk[t][i];
;         *(u32x4*)(wv + t * TSZ + i * 32 * 72) = fv[t][i];
;       }
;   }
;   __syncthreads();
; __device__ void item_nsa(const Params& p, int layer, int b, int g, int qt, unsigned char* smem) {
;     ...
;     flash_pass<true, 1, 2>(hb + C_KS + g * 64, HS, vt, SEQ, 0, kt_end, tilemask, qf, tq, q0, q0 + 31, slope2[0], 0x7fffffff, selq, c1, O, l, sK, sVt);
.LBB0_131:
	v_lshrrev_b32_e32 v36, 4, v37
	v_lshlrev_b32_e32 v39, 7, v2
	v_lshlrev_b32_e32 v2, 4, v2
	v_xor_b32_e32 v40, v36, v37
	v_add3_u32 v153, v39, v2, v0
	v_bfe_u32 v0, v37, 1, 3
	v_and_b32_e32 v3, 15, v37
	v_bfe_u32 v38, v37, 4, 2
	v_lshlrev_b32_e32 v40, 4, v40
	s_movk_i32 s0, 0x70
	v_bitop3_b32 v2, v36, v0, 3 bitop3:0x6c
	v_and_or_b32 v152, v40, s0, v39
	v_lshlrev_b32_e32 v155, 7, v3
	v_mul_u32_u24_e32 v156, 0x90, v3
	v_lshlrev_b32_e32 v157, 4, v2
	v_bitop3_b32 v0, v38, v0, 4 bitop3:0x36
	v_mov_b32_e32 v2, v1
	v_mov_b32_e32 v3, v1
	s_waitcnt lgkmcnt(0)
	s_barrier
	s_waitcnt vmcnt(3)
	ds_write_b128 v152, v[20:23]
	s_waitcnt vmcnt(2)
	ds_write_b128 v153, v[24:27] offset:9216
	s_waitcnt vmcnt(1)
	ds_write_b128 v152, v[28:31] offset:4096
	s_waitcnt vmcnt(0)
	ds_write_b128 v153, v[32:35] offset:13824
	s_mov_b64 s[0:1], 0x20000
	v_lshlrev_b32_e32 v154, 2, v38
	v_lshlrev_b32_e32 v158, 4, v0
	v_mov_b32_e32 v0, v1
	v_mov_b32_e32 v20, 0
	v_mov_b64_e32 v[58:59], v[2:3]
	v_mov_b64_e32 v[38:39], v[2:3]
	v_lshl_add_u64 v[148:149], v[146:147], 0, s[0:1]
	s_mov_b32 s47, 0
	v_mov_b64_e32 v[56:57], v[0:1]
	v_mov_b64_e32 v[36:37], v[0:1]
	v_mov_b32_e32 v21, v20
	v_mov_b32_e32 v22, v20
	v_mov_b32_e32 v23, v20
	v_mov_b32_e32 v24, v20
	v_mov_b32_e32 v25, v20
	v_mov_b32_e32 v26, v20
	v_mov_b32_e32 v27, v20
	v_mov_b32_e32 v28, v20
	v_mov_b32_e32 v29, v20
	v_mov_b32_e32 v30, v20
	v_mov_b32_e32 v31, v20
	v_mov_b32_e32 v32, v20
	v_mov_b32_e32 v33, v20
	v_mov_b32_e32 v34, v20
	v_mov_b32_e32 v35, v20
	v_mov_b32_e32 v40, v20
	v_mov_b32_e32 v41, v20
	v_mov_b32_e32 v42, v20
	v_mov_b32_e32 v43, v20
	v_mov_b32_e32 v44, v20
	v_mov_b32_e32 v45, v20
	v_mov_b32_e32 v46, v20
	v_mov_b32_e32 v47, v20
	v_mov_b32_e32 v48, v20
	v_mov_b32_e32 v49, v20
	v_mov_b32_e32 v50, v20
	v_mov_b32_e32 v51, v20
	v_mov_b32_e32 v52, v20
	v_mov_b32_e32 v53, v20
	v_mov_b32_e32 v54, v20
	v_mov_b32_e32 v55, v20
	s_waitcnt lgkmcnt(0)
	s_barrier
	v_mul_f32_e32 v230, 0x40b17218, v188
	v_mul_f32_e32 v231, 0x3f800000, v230
	v_mul_f32_e32 v232, 0x40000000, v230
	v_mul_f32_e32 v233, 0x40400000, v230
	v_mul_f32_e32 v234, 0x41800000, v230
	v_mul_f32_e32 v235, 0x41880000, v230
	v_mul_f32_e32 v236, 0x41900000, v230
	v_mul_f32_e32 v237, 0x41980000, v230
	v_mul_f32_e32 v242, 0x42000000, v230
	v_mul_f32_e32 v243, 0x42040000, v230
	v_mul_f32_e32 v244, 0x42080000, v230
	v_mul_f32_e32 v245, 0x420c0000, v230
	v_mul_f32_e32 v246, 0x42400000, v230
	v_mul_f32_e32 v247, 0x42440000, v230
	v_mul_f32_e32 v248, 0x42480000, v230
	v_mul_f32_e32 v249, 0x424c0000, v230
	v_mov_b32_e32 v230, 0
	v_add_u32_e32 v164, v155, v157
	v_add_u32_e32 v165, v155, v158
	v_add_u32_e32 v166, v155, v157
	v_add_u32_e32 v167, v155, v158
	v_add_u32_e32 v166, 0x4800, v166
	v_add_u32_e32 v167, 0x4800, v167
	v_lshlrev_b32_e32 v168, 1, v154
	v_add_u32_e32 v168, v168, v156
	v_add_u32_e32 v175, 0x8000, v168
	v_add_u32_e32 v171, 0x3800, v168
	v_add_u32_e32 v174, 0x7800, v168
	v_add_u32_e32 v170, 0x3000, v168
	v_add_u32_e32 v173, 0x7000, v168
	v_add_u32_e32 v169, 0x2800, v168
	v_add_u32_e32 v172, 0x6800, v168
	v_add_u32_e32 v168, 0x2000, v168
	v_mov_b32_e32 v218, s28
	v_mov_b32_e32 v219, s28
	v_mov_b32_e32 v220, s28
	v_mov_b32_e32 v221, s28

;     ...
;     if (k0 <= qhi && (qlo - (k0 + 63)) < window) {
;       bool full = (k0 + 63 <= qlo) && (qhi - k0 < window);
;       const bool rowfull = SEL && full;
;       bool selok[NQ];
; #pragma unroll
;       for (int n = 0; n < NQ; ++n) selok[n] = true;
;       if (SEL) {
;         bool all = true;
; #pragma unroll
;         for (int n = 0; n < NQ; ++n) { selok[n] = ((selq[n] >> kt) & 1u) != 0; all = all && selok[n]; }
;         full = full && __all(all);
;       }
;       const int kbase = k0 + quad * 4;
; #pragma unroll
;       for (int mp = 0; mp < NMAP; ++mp) {
; #pragma unroll
;         for (int n = 0; n < NQ; ++n) {
;           f32x4 S[4];
; #pragma unroll
;           for (int mt = 0; mt < 4; ++mt) S[mt] = f32x4{0.f, 0.f, 0.f, 0.f};
; #pragma unroll
;           for (int ks = 0; ks < 2; ++ks) {
;             if (NMAP == 2 && ks != mp) continue;
; #pragma unroll
;             for (int mt = 0; mt < 4; ++mt) {
;               bf16x8 a = *(const bf16x8*)(cK + (mt * 16 + l15) * 64 + (((ks * 4 + quad) ^ ((l15 >> 1) & 7)) * 8));
;               S[mt] = mfma16(a, qf[n][ks], S[mt]);
;             }
;           }
;           bf16x8 pb[2];
;           const float tb = slope2 * (float)(kbase - tq[n]);
;           if (full || rowfull) {
;             sm_step<false>(S, c1, slope2, tb, kbase, tq[n], window, true, pb);
;             if (SEL && !full && !selok[n]) {
;               pb[0] = bf16x8{0, 0, 0, 0, 0, 0, 0, 0}; pb[1] = bf16x8{0, 0, 0, 0, 0, 0, 0, 0};
;             }
;           } else sm_step<true>(S, c1, slope2, tb, kbase, tq[n], window, selok[n], pb);
.LBB0_141:
	s_and_b64 vcc, exec, s[30:31]
	s_cbranch_vccz .Lsel_slow
	s_cmp_eq_u32 s47, 0
	s_cbranch_scc1 .Lsel_fast0
	s_branch .Lsel_fast1

; __device__ __forceinline__ float fexp2(float x) { return __builtin_amdgcn_exp2f(x); }
; template <bool MASKED>
; __device__ __forceinline__ void sm_step(f32x4 (&S)[4], float c1, float slope2, float tb, int kbase, int tqn,
;                                         int window, bool selok, bf16x8 (&pb)[2]) {
; #pragma unroll
;   for (int mt = 0; mt < 4; ++mt)
; #pragma unroll
;     for (int r = 0; r < 4; ++r) {
;       float u = fmaf(slope2, (float)(mt * 16 + r), fmaf(S[mt][r], c1, tb));
;       if (MASKED) {
;         int dist = tqn - (kbase + mt * 16 + r);
;         bool valid = (dist >= 0) && (dist < window) && selok;
;         u = valid ? u : -1e30f;
;       }
;       S[mt][r] = fexp2(u);
;     }
; #pragma unroll
;   for (int k2 = 0; k2 < 2; ++k2)
;     pb[k2] = pack8(S[2 * k2][0], S[2 * k2][1], S[2 * k2][2], S[2 * k2][3],
;                    S[2 * k2 + 1][0], S[2 * k2 + 1][1], S[2 * k2 + 1][2], S[2 * k2 + 1][3]);
;     ...
; #pragma unroll
;       for (int mp = 0; mp < NMAP; ++mp) {
; #pragma unroll
;         for (int n = 0; n < NQ; ++n) {
;           f32x4 S[4];
; #pragma unroll
;           for (int mt = 0; mt < 4; ++mt) S[mt] = f32x4{0.f, 0.f, 0.f, 0.f};
; #pragma unroll
;           for (int ks = 0; ks < 2; ++ks) {
;             if (NMAP == 2 && ks != mp) continue;
; #pragma unroll
;             for (int mt = 0; mt < 4; ++mt) {
;               bf16x8 a = *(const bf16x8*)(cK + (mt * 16 + l15) * 64 + (((ks * 4 + quad) ^ ((l15 >> 1) & 7)) * 8));
;               S[mt] = mfma16(a, qf[n][ks], S[mt]);
;             }
;           }
;           bf16x8 pb[2];
;           const float tb = slope2 * (float)(kbase - tq[n]);
;           if (full || rowfull) {
;             sm_step<false>(S, c1, slope2, tb, kbase, tq[n], window, true, pb);
;             if (SEL && !full && !selok[n]) {
;               pb[0] = bf16x8{0, 0, 0, 0, 0, 0, 0, 0}; pb[1] = bf16x8{0, 0, 0, 0, 0, 0, 0, 0};
;             }
;           } else sm_step<true>(S, c1, slope2, tb, kbase, tq[n], window, selok[n], pb);
; #pragma unroll
;           for (int k2 = 0; k2 < 2; ++k2) {
; #pragma unroll
;             for (int dt = 0; dt < 4; ++dt) {
;               bf16x8 a = vt_frag(cV, dt, k2, l15, quad);
;               O[mp * NQ + n][dt] = mfma16(a, pb[k2], O[mp * NQ + n][dt]);
;             }
;             L[mp * NQ + n] = mfma16(ones, pb[k2], L[mp * NQ + n]);
;           }
.Lsel_fast0:
	v_or_b32_e32 v0, s42, v154
	s_or_b64 s[40:41], s[40:41], s[18:19]
	s_or_b64 s[38:39], s[38:39], s[18:19]
	v_sub_u32_e32 v2, v0, v200
	v_cvt_f32_i32_e32 v2, v2
	v_mul_f32_e32 v159, v188, v2
	v_sub_u32_e32 v2, v0, v201
	v_cvt_f32_i32_e32 v2, v2
	v_mul_f32_e32 v186, v188, v2
	ds_read_b128 v[76:79], v164
	ds_read_b128 v[80:83], v164 offset:2048
	ds_read_b128 v[84:87], v164 offset:4096
	ds_read_b128 v[88:91], v164 offset:6144
	ds_read_b128 v[92:95], v165
	ds_read_b128 v[96:99], v165 offset:2048
	ds_read_b128 v[100:103], v165 offset:4096
	ds_read_b128 v[104:107], v165 offset:6144
	ds_read2_b64 v[108:111], v168 offset0:128 offset1:132
	ds_read2_b64 v[112:115], v169 offset0:160 offset1:164
	ds_read2_b64 v[116:119], v170 offset0:192 offset1:196
	ds_read2_b64 v[120:123], v171 offset0:224 offset1:228
	v_cndmask_b32_e64 v159, v226, v159, s[40:41]
	v_cndmask_b32_e64 v186, v226, v186, s[38:39]
	s_waitcnt lgkmcnt(11)
	v_mfma_f32_16x16x32_bf16 v[124:127], v[76:79], v[4:7], v[230:233]
	s_waitcnt lgkmcnt(10)
	v_mfma_f32_16x16x32_bf16 v[128:131], v[80:83], v[4:7], v[234:237]
	s_waitcnt lgkmcnt(9)
	v_mfma_f32_16x16x32_bf16 v[132:135], v[84:87], v[4:7], v[242:245]
	s_waitcnt lgkmcnt(8)
	v_mfma_f32_16x16x32_bf16 v[136:139], v[88:91], v[4:7], v[246:249]
	s_waitcnt lgkmcnt(7)
	v_mfma_f32_16x16x32_bf16 v[124:127], v[92:95], v[8:11], v[124:127]
	s_waitcnt lgkmcnt(6)
	v_mfma_f32_16x16x32_bf16 v[128:131], v[96:99], v[8:11], v[128:131]
	s_waitcnt lgkmcnt(5)
	v_mfma_f32_16x16x32_bf16 v[132:135], v[100:103], v[8:11], v[132:135]
	s_waitcnt lgkmcnt(4)
	v_mfma_f32_16x16x32_bf16 v[136:139], v[104:107], v[8:11], v[136:139]
	s_nop 1
	v_fmamk_f32 v124, v124, 0x3e38aa3b, v159
	v_fmamk_f32 v125, v125, 0x3e38aa3b, v159
	v_fmamk_f32 v126, v126, 0x3e38aa3b, v159
	v_fmamk_f32 v127, v127, 0x3e38aa3b, v159
	v_fmamk_f32 v128, v128, 0x3e38aa3b, v159
	v_mfma_f32_16x16x32_bf16 v[140:143], v[76:79], v[12:15], v[230:233]
	v_fmamk_f32 v129, v129, 0x3e38aa3b, v159
	v_fmamk_f32 v130, v130, 0x3e38aa3b, v159
	v_fmamk_f32 v131, v131, 0x3e38aa3b, v159
	v_exp_f32_e32 v124, v124
	v_mfma_f32_16x16x32_bf16 v[160:163], v[80:83], v[12:15], v[234:237]
	v_exp_f32_e32 v125, v125
	v_exp_f32_e32 v126, v126
	v_mfma_f32_16x16x32_bf16 v[176:179], v[84:87], v[12:15], v[242:245]
	v_exp_f32_e32 v127, v127
	v_fmamk_f32 v132, v132, 0x3e38aa3b, v159
	v_mfma_f32_16x16x32_bf16 v[194:197], v[88:91], v[12:15], v[246:249]
	v_fmamk_f32 v133, v133, 0x3e38aa3b, v159
	v_fmamk_f32 v134, v134, 0x3e38aa3b, v159
	v_fmamk_f32 v135, v135, 0x3e38aa3b, v159
	v_exp_f32_e32 v128, v128
	v_mfma_f32_16x16x32_bf16 v[140:143], v[92:95], v[16:19], v[140:143]
	v_exp_f32_e32 v129, v129
	v_mfma_f32_16x16x32_bf16 v[160:163], v[96:99], v[16:19], v[160:163]
	v_exp_f32_e32 v130, v130
	v_exp_f32_e32 v131, v131
	v_mfma_f32_16x16x32_bf16 v[176:179], v[100:103], v[16:19], v[176:179]
	v_cvt_pk_bf16_f32 v222, v124, v125
	v_cvt_pk_bf16_f32 v223, v126, v127
	v_fmamk_f32 v136, v136, 0x3e38aa3b, v159
	v_fmamk_f32 v137, v137, 0x3e38aa3b, v159
	v_mfma_f32_16x16x32_bf16 v[194:197], v[104:107], v[16:19], v[194:197]
	ds_read2_b64 v[76:79], v168 offset0:136 offset1:140
	ds_read2_b64 v[80:83], v169 offset0:168 offset1:172
	ds_read2_b64 v[84:87], v170 offset0:200 offset1:204
	ds_read2_b64 v[88:91], v171 offset0:232 offset1:236
	v_fmamk_f32 v138, v138, 0x3e38aa3b, v159
	v_fmamk_f32 v139, v139, 0x3e38aa3b, v159
	v_exp_f32_e32 v132, v132
	v_exp_f32_e32 v133, v133
	v_exp_f32_e32 v134, v134
	v_exp_f32_e32 v135, v135
	v_cvt_pk_bf16_f32 v224, v128, v129
	v_cvt_pk_bf16_f32 v225, v130, v131
	v_exp_f32_e32 v136, v136
	v_exp_f32_e32 v137, v137
	v_exp_f32_e32 v138, v138
	v_exp_f32_e32 v139, v139
	v_cvt_pk_bf16_f32 v238, v132, v133
	v_cvt_pk_bf16_f32 v239, v134, v135
	v_cvt_pk_bf16_f32 v240, v136, v137
	v_cvt_pk_bf16_f32 v241, v138, v139
	v_fmamk_f32 v140, v140, 0x3e38aa3b, v186
	v_fmamk_f32 v141, v141, 0x3e38aa3b, v186
	v_fmamk_f32 v142, v142, 0x3e38aa3b, v186
	v_fmamk_f32 v143, v143, 0x3e38aa3b, v186
	v_fmamk_f32 v160, v160, 0x3e38aa3b, v186
	s_waitcnt lgkmcnt(7)
	v_mfma_f32_16x16x32_bf16 v[52:55], v[108:111], v[222:225], v[52:55]
	v_fmamk_f32 v161, v161, 0x3e38aa3b, v186
	v_fmamk_f32 v162, v162, 0x3e38aa3b, v186
	v_fmamk_f32 v163, v163, 0x3e38aa3b, v186
	v_exp_f32_e32 v140, v140
	v_exp_f32_e32 v141, v141
	s_waitcnt lgkmcnt(6)
	v_mfma_f32_16x16x32_bf16 v[48:51], v[112:115], v[222:225], v[48:51]
	v_exp_f32_e32 v142, v142
	v_exp_f32_e32 v143, v143
	s_waitcnt lgkmcnt(5)
	v_mfma_f32_16x16x32_bf16 v[44:47], v[116:119], v[222:225], v[44:47]
	v_fmamk_f32 v176, v176, 0x3e38aa3b, v186
	v_fmamk_f32 v177, v177, 0x3e38aa3b, v186
	v_fmamk_f32 v178, v178, 0x3e38aa3b, v186
	v_fmamk_f32 v179, v179, 0x3e38aa3b, v186
	v_exp_f32_e32 v160, v160
	s_waitcnt lgkmcnt(4)
	v_mfma_f32_16x16x32_bf16 v[40:43], v[120:123], v[222:225], v[40:43]
	v_exp_f32_e32 v161, v161
	v_exp_f32_e32 v162, v162
	v_mfma_f32_16x16x32_bf16 v[56:59], v[218:221], v[222:225], v[56:59]
	v_exp_f32_e32 v163, v163
	v_cvt_pk_bf16_f32 v100, v140, v141
	v_cvt_pk_bf16_f32 v101, v142, v143
	v_fmamk_f32 v194, v194, 0x3e38aa3b, v186
	s_waitcnt lgkmcnt(3)
	v_mfma_f32_16x16x32_bf16 v[52:55], v[76:79], v[238:241], v[52:55]
	v_fmamk_f32 v195, v195, 0x3e38aa3b, v186
	v_fmamk_f32 v196, v196, 0x3e38aa3b, v186
	v_fmamk_f32 v197, v197, 0x3e38aa3b, v186
	v_exp_f32_e32 v176, v176
	v_exp_f32_e32 v177, v177
	s_waitcnt lgkmcnt(2)
	v_mfma_f32_16x16x32_bf16 v[48:51], v[80:83], v[238:241], v[48:51]
	v_exp_f32_e32 v178, v178
	v_exp_f32_e32 v179, v179
	s_waitcnt lgkmcnt(1)
	v_mfma_f32_16x16x32_bf16 v[44:47], v[84:87], v[238:241], v[44:47]
	v_cvt_pk_bf16_f32 v102, v160, v161
	v_cvt_pk_bf16_f32 v103, v162, v163
	v_exp_f32_e32 v194, v194
	v_exp_f32_e32 v195, v195
	s_waitcnt lgkmcnt(0)
	v_mfma_f32_16x16x32_bf16 v[40:43], v[88:91], v[238:241], v[40:43]
	v_exp_f32_e32 v196, v196
	v_exp_f32_e32 v197, v197
	v_mfma_f32_16x16x32_bf16 v[56:59], v[218:221], v[238:241], v[56:59]
	v_cvt_pk_bf16_f32 v104, v176, v177
	v_cvt_pk_bf16_f32 v105, v178, v179
	v_cvt_pk_bf16_f32 v106, v194, v195
	v_cvt_pk_bf16_f32 v107, v196, v197
	v_mfma_f32_16x16x32_bf16 v[32:35], v[108:111], v[100:103], v[32:35]
	v_mfma_f32_16x16x32_bf16 v[28:31], v[112:115], v[100:103], v[28:31]
	v_mfma_f32_16x16x32_bf16 v[24:27], v[116:119], v[100:103], v[24:27]
	v_mfma_f32_16x16x32_bf16 v[20:23], v[120:123], v[100:103], v[20:23]
	v_mfma_f32_16x16x32_bf16 v[36:39], v[218:221], v[100:103], v[36:39]
	v_mfma_f32_16x16x32_bf16 v[32:35], v[76:79], v[104:107], v[32:35]
	v_mfma_f32_16x16x32_bf16 v[28:31], v[80:83], v[104:107], v[28:31]
	v_mfma_f32_16x16x32_bf16 v[24:27], v[84:87], v[104:107], v[24:27]
	v_mfma_f32_16x16x32_bf16 v[20:23], v[88:91], v[104:107], v[20:23]
	v_mfma_f32_16x16x32_bf16 v[36:39], v[218:221], v[104:107], v[36:39]
	s_nop 1
	s_branch .LBB0_154
; __device__ __forceinline__ float fexp2(float x) { return __builtin_amdgcn_exp2f(x); }
; template <bool MASKED>
; __device__ __forceinline__ void sm_step(f32x4 (&S)[4], float c1, float slope2, float tb, int kbase, int tqn,
;                                         int window, bool selok, bf16x8 (&pb)[2]) {
; #pragma unroll
;   for (int mt = 0; mt < 4; ++mt)
; #pragma unroll
;     for (int r = 0; r < 4; ++r) {
;       float u = fmaf(slope2, (float)(mt * 16 + r), fmaf(S[mt][r], c1, tb));
;       if (MASKED) {
;         int dist = tqn - (kbase + mt * 16 + r);
;         bool valid = (dist >= 0) && (dist < window) && selok;
;         u = valid ? u : -1e30f;
;       }
;       S[mt][r] = fexp2(u);
;     }
; #pragma unroll
;   for (int k2 = 0; k2 < 2; ++k2)
;     pb[k2] = pack8(S[2 * k2][0], S[2 * k2][1], S[2 * k2][2], S[2 * k2][3],
;                    S[2 * k2 + 1][0], S[2 * k2 + 1][1], S[2 * k2 + 1][2], S[2 * k2 + 1][3]);
;     ...
; #pragma unroll
;       for (int mp = 0; mp < NMAP; ++mp) {
; #pragma unroll
;         for (int n = 0; n < NQ; ++n) {
;           f32x4 S[4];
; #pragma unroll
;           for (int mt = 0; mt < 4; ++mt) S[mt] = f32x4{0.f, 0.f, 0.f, 0.f};
; #pragma unroll
;           for (int ks = 0; ks < 2; ++ks) {
;             if (NMAP == 2 && ks != mp) continue;
; #pragma unroll
;             for (int mt = 0; mt < 4; ++mt) {
;               bf16x8 a = *(const bf16x8*)(cK + (mt * 16 + l15) * 64 + (((ks * 4 + quad) ^ ((l15 >> 1) & 7)) * 8));
;               S[mt] = mfma16(a, qf[n][ks], S[mt]);
;             }
;           }
;           bf16x8 pb[2];
;           const float tb = slope2 * (float)(kbase - tq[n]);
;           if (full || rowfull) {
;             sm_step<false>(S, c1, slope2, tb, kbase, tq[n], window, true, pb);
;             if (SEL && !full && !selok[n]) {
;               pb[0] = bf16x8{0, 0, 0, 0, 0, 0, 0, 0}; pb[1] = bf16x8{0, 0, 0, 0, 0, 0, 0, 0};
;             }
;           } else sm_step<true>(S, c1, slope2, tb, kbase, tq[n], window, selok[n], pb);
; #pragma unroll
;           for (int k2 = 0; k2 < 2; ++k2) {
; #pragma unroll
;             for (int dt = 0; dt < 4; ++dt) {
;               bf16x8 a = vt_frag(cV, dt, k2, l15, quad);
;               O[mp * NQ + n][dt] = mfma16(a, pb[k2], O[mp * NQ + n][dt]);
;             }
;             L[mp * NQ + n] = mfma16(ones, pb[k2], L[mp * NQ + n]);
;           }
.Lsel_fast1:
	v_or_b32_e32 v0, s42, v154
	s_or_b64 s[40:41], s[40:41], s[18:19]
	s_or_b64 s[38:39], s[38:39], s[18:19]
	v_sub_u32_e32 v2, v0, v200
	v_cvt_f32_i32_e32 v2, v2
	v_mul_f32_e32 v159, v188, v2
	v_sub_u32_e32 v2, v0, v201
	v_cvt_f32_i32_e32 v2, v2
	v_mul_f32_e32 v186, v188, v2
	ds_read_b128 v[76:79], v166
	ds_read_b128 v[80:83], v166 offset:2048
	ds_read_b128 v[84:87], v166 offset:4096
	ds_read_b128 v[88:91], v166 offset:6144
	ds_read_b128 v[92:95], v167
	ds_read_b128 v[96:99], v167 offset:2048
	ds_read_b128 v[100:103], v167 offset:4096
	ds_read_b128 v[104:107], v167 offset:6144
	ds_read2_b64 v[108:111], v172 offset0:128 offset1:132
	ds_read2_b64 v[112:115], v173 offset0:160 offset1:164
	ds_read2_b64 v[116:119], v174 offset0:192 offset1:196
	ds_read2_b64 v[120:123], v175 offset0:224 offset1:228
	v_cndmask_b32_e64 v159, v226, v159, s[40:41]
	v_cndmask_b32_e64 v186, v226, v186, s[38:39]
	s_waitcnt lgkmcnt(11)
	v_mfma_f32_16x16x32_bf16 v[124:127], v[76:79], v[4:7], v[230:233]
	s_waitcnt lgkmcnt(10)
	v_mfma_f32_16x16x32_bf16 v[128:131], v[80:83], v[4:7], v[234:237]
	s_waitcnt lgkmcnt(9)
	v_mfma_f32_16x16x32_bf16 v[132:135], v[84:87], v[4:7], v[242:245]
	s_waitcnt lgkmcnt(8)
	v_mfma_f32_16x16x32_bf16 v[136:139], v[88:91], v[4:7], v[246:249]
	s_waitcnt lgkmcnt(7)
	v_mfma_f32_16x16x32_bf16 v[124:127], v[92:95], v[8:11], v[124:127]
	s_waitcnt lgkmcnt(6)
	v_mfma_f32_16x16x32_bf16 v[128:131], v[96:99], v[8:11], v[128:131]
	s_waitcnt lgkmcnt(5)
	v_mfma_f32_16x16x32_bf16 v[132:135], v[100:103], v[8:11], v[132:135]
	s_waitcnt lgkmcnt(4)
	v_mfma_f32_16x16x32_bf16 v[136:139], v[104:107], v[8:11], v[136:139]
	s_nop 1
	v_fmamk_f32 v124, v124, 0x3e38aa3b, v159
	v_fmamk_f32 v125, v125, 0x3e38aa3b, v159
	v_fmamk_f32 v126, v126, 0x3e38aa3b, v159
	v_fmamk_f32 v127, v127, 0x3e38aa3b, v159
	v_fmamk_f32 v128, v128, 0x3e38aa3b, v159
	v_mfma_f32_16x16x32_bf16 v[140:143], v[76:79], v[12:15], v[230:233]
	v_fmamk_f32 v129, v129, 0x3e38aa3b, v159
	v_fmamk_f32 v130, v130, 0x3e38aa3b, v159
	v_fmamk_f32 v131, v131, 0x3e38aa3b, v159
	v_exp_f32_e32 v124, v124
	v_mfma_f32_16x16x32_bf16 v[160:163], v[80:83], v[12:15], v[234:237]
	v_exp_f32_e32 v125, v125
	v_exp_f32_e32 v126, v126
	v_mfma_f32_16x16x32_bf16 v[176:179], v[84:87], v[12:15], v[242:245]
	v_exp_f32_e32 v127, v127
	v_fmamk_f32 v132, v132, 0x3e38aa3b, v159
	v_mfma_f32_16x16x32_bf16 v[194:197], v[88:91], v[12:15], v[246:249]
	v_fmamk_f32 v133, v133, 0x3e38aa3b, v159
	v_fmamk_f32 v134, v134, 0x3e38aa3b, v159
	v_fmamk_f32 v135, v135, 0x3e38aa3b, v159
	v_exp_f32_e32 v128, v128
	v_mfma_f32_16x16x32_bf16 v[140:143], v[92:95], v[16:19], v[140:143]
	v_exp_f32_e32 v129, v129
	v_mfma_f32_16x16x32_bf16 v[160:163], v[96:99], v[16:19], v[160:163]
	v_exp_f32_e32 v130, v130
	v_exp_f32_e32 v131, v131
	v_mfma_f32_16x16x32_bf16 v[176:179], v[100:103], v[16:19], v[176:179]
	v_cvt_pk_bf16_f32 v222, v124, v125
	v_cvt_pk_bf16_f32 v223, v126, v127
	v_fmamk_f32 v136, v136, 0x3e38aa3b, v159
	v_fmamk_f32 v137, v137, 0x3e38aa3b, v159
	v_mfma_f32_16x16x32_bf16 v[194:197], v[104:107], v[16:19], v[194:197]
	ds_read2_b64 v[76:79], v172 offset0:136 offset1:140
	ds_read2_b64 v[80:83], v173 offset0:168 offset1:172
	ds_read2_b64 v[84:87], v174 offset0:200 offset1:204
	ds_read2_b64 v[88:91], v175 offset0:232 offset1:236
	v_fmamk_f32 v138, v138, 0x3e38aa3b, v159
	v_fmamk_f32 v139, v139, 0x3e38aa3b, v159
	v_exp_f32_e32 v132, v132
	v_exp_f32_e32 v133, v133
	v_exp_f32_e32 v134, v134
	v_exp_f32_e32 v135, v135
	v_cvt_pk_bf16_f32 v224, v128, v129
	v_cvt_pk_bf16_f32 v225, v130, v131
	v_exp_f32_e32 v136, v136
	v_exp_f32_e32 v137, v137
	v_exp_f32_e32 v138, v138
	v_exp_f32_e32 v139, v139
	v_cvt_pk_bf16_f32 v238, v132, v133
	v_cvt_pk_bf16_f32 v239, v134, v135
	v_cvt_pk_bf16_f32 v240, v136, v137
	v_cvt_pk_bf16_f32 v241, v138, v139
	v_fmamk_f32 v140, v140, 0x3e38aa3b, v186
	v_fmamk_f32 v141, v141, 0x3e38aa3b, v186
	v_fmamk_f32 v142, v142, 0x3e38aa3b, v186
	v_fmamk_f32 v143, v143, 0x3e38aa3b, v186
	v_fmamk_f32 v160, v160, 0x3e38aa3b, v186
	s_waitcnt lgkmcnt(7)
	v_mfma_f32_16x16x32_bf16 v[52:55], v[108:111], v[222:225], v[52:55]
	v_fmamk_f32 v161, v161, 0x3e38aa3b, v186
	v_fmamk_f32 v162, v162, 0x3e38aa3b, v186
	v_fmamk_f32 v163, v163, 0x3e38aa3b, v186
	v_exp_f32_e32 v140, v140
	v_exp_f32_e32 v141, v141
	s_waitcnt lgkmcnt(6)
	v_mfma_f32_16x16x32_bf16 v[48:51], v[112:115], v[222:225], v[48:51]
	v_exp_f32_e32 v142, v142
	v_exp_f32_e32 v143, v143
	s_waitcnt lgkmcnt(5)
	v_mfma_f32_16x16x32_bf16 v[44:47], v[116:119], v[222:225], v[44:47]
	v_fmamk_f32 v176, v176, 0x3e38aa3b, v186
	v_fmamk_f32 v177, v177, 0x3e38aa3b, v186
	v_fmamk_f32 v178, v178, 0x3e38aa3b, v186
	v_fmamk_f32 v179, v179, 0x3e38aa3b, v186
	v_exp_f32_e32 v160, v160
	s_waitcnt lgkmcnt(4)
	v_mfma_f32_16x16x32_bf16 v[40:43], v[120:123], v[222:225], v[40:43]
	v_exp_f32_e32 v161, v161
	v_exp_f32_e32 v162, v162
	v_mfma_f32_16x16x32_bf16 v[56:59], v[218:221], v[222:225], v[56:59]
	v_exp_f32_e32 v163, v163
	v_cvt_pk_bf16_f32 v100, v140, v141
	v_cvt_pk_bf16_f32 v101, v142, v143
	v_fmamk_f32 v194, v194, 0x3e38aa3b, v186
	s_waitcnt lgkmcnt(3)
	v_mfma_f32_16x16x32_bf16 v[52:55], v[76:79], v[238:241], v[52:55]
	v_fmamk_f32 v195, v195, 0x3e38aa3b, v186
	v_fmamk_f32 v196, v196, 0x3e38aa3b, v186
	v_fmamk_f32 v197, v197, 0x3e38aa3b, v186
	v_exp_f32_e32 v176, v176
	v_exp_f32_e32 v177, v177
	s_waitcnt lgkmcnt(2)
	v_mfma_f32_16x16x32_bf16 v[48:51], v[80:83], v[238:241], v[48:51]
	v_exp_f32_e32 v178, v178
	v_exp_f32_e32 v179, v179
	s_waitcnt lgkmcnt(1)
	v_mfma_f32_16x16x32_bf16 v[44:47], v[84:87], v[238:241], v[44:47]
	v_cvt_pk_bf16_f32 v102, v160, v161
	v_cvt_pk_bf16_f32 v103, v162, v163
	v_exp_f32_e32 v194, v194
	v_exp_f32_e32 v195, v195
	s_waitcnt lgkmcnt(0)
	v_mfma_f32_16x16x32_bf16 v[40:43], v[88:91], v[238:241], v[40:43]
	v_exp_f32_e32 v196, v196
	v_exp_f32_e32 v197, v197
	v_mfma_f32_16x16x32_bf16 v[56:59], v[218:221], v[238:241], v[56:59]
	v_cvt_pk_bf16_f32 v104, v176, v177
	v_cvt_pk_bf16_f32 v105, v178, v179
	v_cvt_pk_bf16_f32 v106, v194, v195
	v_cvt_pk_bf16_f32 v107, v196, v197
	v_mfma_f32_16x16x32_bf16 v[32:35], v[108:111], v[100:103], v[32:35]
	v_mfma_f32_16x16x32_bf16 v[28:31], v[112:115], v[100:103], v[28:31]
	v_mfma_f32_16x16x32_bf16 v[24:27], v[116:119], v[100:103], v[24:27]
	v_mfma_f32_16x16x32_bf16 v[20:23], v[120:123], v[100:103], v[20:23]
	v_mfma_f32_16x16x32_bf16 v[36:39], v[218:221], v[100:103], v[36:39]
	v_mfma_f32_16x16x32_bf16 v[32:35], v[76:79], v[104:107], v[32:35]
	v_mfma_f32_16x16x32_bf16 v[28:31], v[80:83], v[104:107], v[28:31]
	v_mfma_f32_16x16x32_bf16 v[24:27], v[84:87], v[104:107], v[24:27]
	v_mfma_f32_16x16x32_bf16 v[20:23], v[88:91], v[104:107], v[20:23]
	v_mfma_f32_16x16x32_bf16 v[36:39], v[218:221], v[104:107], v[36:39]
	s_nop 1
	s_branch .LBB0_154
